# adds: P5 residual epilogue f32 base-row loads issued 16 at a time per 128-row half
# speedup vs baseline: 1.0038x; 1.0018x over previous
;     __device__ __forceinline__ void operator()(const f32x4 (&acc)[2][2][4][2], const Unit& u, int wr, int wc, int fr, int fq) const {
;     ...
;             for (int m = 0; m < 4; ++m) { const int row = row0 + ai * HALF + m * 16;
; #pragma unroll
;                 for (int bj = 0; bj < 2; ++bj) { const int col = col0 + bj * HALF;
;                     if (u.split) { float* pp = part + ((size_t)(u.k0 / u.nt) * (MROWS - MP) + (size_t)(row - MP)) * 2048 + col;
;                         *(f32x4*)pp = g[bj][0] * acc[ai][bj][m][0]; *(f32x4*)(pp + 4) = g[bj][1] * acc[ai][bj][m][1];
;                     } else {
;                         f32x4 b0, b1;
;                         if (xp) { const float* src = xp + (size_t)row * 2048 + col; b0 = *(const f32x4*)src; b1 = *(const f32x4*)(src + 4); }
.LBB0_531:
	s_andn2_b64 vcc, exec, s[22:23]
	s_cbranch_vccnz .LBB0_647
	v_lshl_add_u64 v[248:249], s[36:37], 0, v[172:173]
	v_lshl_add_u64 v[248:249], v[166:167], 2, v[248:249]
	global_load_dwordx4 v[184:187], v[248:249], off offset:16
	global_load_dwordx4 v[188:191], v[248:249], off
	global_load_dwordx4 v[192:195], v[248:249], off offset:528
	global_load_dwordx4 v[196:199], v[248:249], off offset:512
	v_add_co_u32_e32 v248, vcc, 0x20000, v248
	s_nop 1
	v_addc_co_u32_e32 v249, vcc, 0, v249, vcc
	global_load_dwordx4 v[200:203], v[248:249], off offset:16
	global_load_dwordx4 v[204:207], v[248:249], off
	global_load_dwordx4 v[208:211], v[248:249], off offset:528
	global_load_dwordx4 v[212:215], v[248:249], off offset:512
	v_add_co_u32_e32 v248, vcc, 0x20000, v248
	s_nop 1
	v_addc_co_u32_e32 v249, vcc, 0, v249, vcc
	global_load_dwordx4 v[216:219], v[248:249], off offset:16
	global_load_dwordx4 v[220:223], v[248:249], off
	global_load_dwordx4 v[224:227], v[248:249], off offset:528
	global_load_dwordx4 v[228:231], v[248:249], off offset:512
	v_add_co_u32_e32 v248, vcc, 0x20000, v248
	s_nop 1
	v_addc_co_u32_e32 v249, vcc, 0, v249, vcc
	global_load_dwordx4 v[232:235], v[248:249], off offset:16
	global_load_dwordx4 v[236:239], v[248:249], off
	global_load_dwordx4 v[240:243], v[248:249], off offset:528
	global_load_dwordx4 v[244:247], v[248:249], off offset:512
	v_lshl_add_u64 v[144:145], s[36:37], 0, v[172:173]
	v_lshl_add_u64 v[144:145], v[166:167], 2, v[144:145]
	s_nop 0
	s_nop 0
	s_nop 0
	s_cbranch_execnz .LBB0_534

; __device__ __forceinline__ u32x4 pack8(f32x4 v0, f32x4 v1) { u32x4 w; w.x = cvt_pk_bf16(v0[0], v0[1]); w.y = cvt_pk_bf16(v0[2], v0[3]); w.z = cvt_pk_bf16(v1[0], v1[1]); w.w = cvt_pk_bf16(v1[2], v1[3]); return w; }
;     __device__ __forceinline__ void operator()(const f32x4 (&acc)[2][2][4][2], const Unit& u, int wr, int wc, int fr, int fq) const {
;     ...
;                 for (int bj = 0; bj < 2; ++bj) { const int col = col0 + bj * HALF;
;                     if (u.split) { float* pp = part + ((size_t)(u.k0 / u.nt) * (MROWS - MP) + (size_t)(row - MP)) * 2048 + col;
;                         *(f32x4*)pp = g[bj][0] * acc[ai][bj][m][0]; *(f32x4*)(pp + 4) = g[bj][1] * acc[ai][bj][m][1];
;                     } else {
;                         f32x4 b0, b1;
;                         if (xp) { const float* src = xp + (size_t)row * 2048 + col; b0 = *(const f32x4*)src; b1 = *(const f32x4*)(src + 4); }
;                         else { const u32x4 w = *(const u32x4*)(baseb + (size_t)row * 2048 + col);
;                             b0 = (f32x4){__builtin_bit_cast(float, w.x << 16), __builtin_bit_cast(float, w.x & 0xffff0000u), __builtin_bit_cast(float, w.y << 16), __builtin_bit_cast(float, w.y & 0xffff0000u)};
;                             b1 = (f32x4){__builtin_bit_cast(float, w.z << 16), __builtin_bit_cast(float, w.z & 0xffff0000u), __builtin_bit_cast(float, w.w << 16), __builtin_bit_cast(float, w.w & 0xffff0000u)}; }
;                         *(u32x4*)(outb + (size_t)row * 2048 + col) = pack8(b0 + g[bj][0] * acc[ai][bj][m][0], b1 + g[bj][1] * acc[ai][bj][m][1]); } } }
.LBB0_534:
	s_waitcnt vmcnt(14)
	v_pk_fma_f32 v[140:141], v[140:141], v[124:125], v[188:189]
	v_pk_fma_f32 v[144:145], v[138:139], v[118:119], v[186:187]
	v_pk_fma_f32 v[138:139], v[136:137], v[116:117], v[184:185]
	v_cvt_pk_bf16_f32 v136, v140, v141
	v_lshl_add_u64 v[140:141], s[12:13], 0, v[170:171]
	v_lshl_add_u64 v[140:141], v[166:167], 1, v[140:141]
	v_pk_fma_f32 v[142:143], v[142:143], v[126:127], v[190:191]
	s_nop 0
	v_cvt_pk_bf16_f32 v137, v142, v143
	v_cvt_pk_bf16_f32 v138, v138, v139
	v_cvt_pk_bf16_f32 v139, v144, v145
	global_store_dwordx4 v[140:141], v[136:139], off
	s_nop 1
	v_cndmask_b32_e64 v136, 0, 1, s[60:61]
	v_cmp_ne_u32_e64 s[4:5], 1, v136
	s_andn2_b64 vcc, exec, s[60:61]
	s_cbranch_vccz .LBB0_527
.LBB0_535:
.LBB0_536:
	s_andn2_b64 vcc, exec, s[22:23]
	s_cbranch_vccnz .LBB0_648
	v_lshl_add_u64 v[136:137], s[36:37], 0, v[172:173]
	v_lshl_add_u64 v[136:137], v[166:167], 2, v[136:137]
	s_nop 0
	s_nop 0
	s_nop 0
	s_cbranch_execnz .LBB0_539

; __device__ __forceinline__ u32x4 pack8(f32x4 v0, f32x4 v1) { u32x4 w; w.x = cvt_pk_bf16(v0[0], v0[1]); w.y = cvt_pk_bf16(v0[2], v0[3]); w.z = cvt_pk_bf16(v1[0], v1[1]); w.w = cvt_pk_bf16(v1[2], v1[3]); return w; }
;     __device__ __forceinline__ void operator()(const f32x4 (&acc)[2][2][4][2], const Unit& u, int wr, int wc, int fr, int fq) const {
;     ...
;                 for (int bj = 0; bj < 2; ++bj) { const int col = col0 + bj * HALF;
;                     if (u.split) { float* pp = part + ((size_t)(u.k0 / u.nt) * (MROWS - MP) + (size_t)(row - MP)) * 2048 + col;
;                         *(f32x4*)pp = g[bj][0] * acc[ai][bj][m][0]; *(f32x4*)(pp + 4) = g[bj][1] * acc[ai][bj][m][1];
;                     } else {
;                         f32x4 b0, b1;
;                         if (xp) { const float* src = xp + (size_t)row * 2048 + col; b0 = *(const f32x4*)src; b1 = *(const f32x4*)(src + 4); }
;                         else { const u32x4 w = *(const u32x4*)(baseb + (size_t)row * 2048 + col);
;                             b0 = (f32x4){__builtin_bit_cast(float, w.x << 16), __builtin_bit_cast(float, w.x & 0xffff0000u), __builtin_bit_cast(float, w.y << 16), __builtin_bit_cast(float, w.y & 0xffff0000u)};
;                             b1 = (f32x4){__builtin_bit_cast(float, w.z << 16), __builtin_bit_cast(float, w.z & 0xffff0000u), __builtin_bit_cast(float, w.w << 16), __builtin_bit_cast(float, w.w & 0xffff0000u)}; }
;                         *(u32x4*)(outb + (size_t)row * 2048 + col) = pack8(b0 + g[bj][0] * acc[ai][bj][m][0], b1 + g[bj][1] * acc[ai][bj][m][1]); } } }
.LBB0_539:
	s_waitcnt vmcnt(13)
	v_pk_fma_f32 v[132:133], v[132:133], v[108:109], v[196:197]
	v_pk_fma_f32 v[136:137], v[130:131], v[106:107], v[194:195]
	v_pk_fma_f32 v[130:131], v[128:129], v[104:105], v[192:193]
	v_cvt_pk_bf16_f32 v128, v132, v133
	v_lshl_add_u64 v[132:133], s[12:13], 0, v[170:171]
	v_lshl_add_u64 v[132:133], v[166:167], 1, v[132:133]
	v_pk_fma_f32 v[134:135], v[134:135], v[110:111], v[198:199]
	s_nop 0
	v_cvt_pk_bf16_f32 v129, v134, v135
	v_cvt_pk_bf16_f32 v130, v130, v131
	v_cvt_pk_bf16_f32 v131, v136, v137
	global_store_dwordx4 v[132:133], v[128:131], off offset:256
	s_nop 1
	v_lshlrev_b64 v[128:129], 13, v[168:169]
	s_and_b64 vcc, exec, s[4:5]
	v_lshl_add_u64 v[138:139], v[128:129], 0, s[26:27]
	s_cbranch_vccz .LBB0_529

;     __device__ __forceinline__ void operator()(const f32x4 (&acc)[2][2][4][2], const Unit& u, int wr, int wc, int fr, int fq) const {
;     ...
;             for (int m = 0; m < 4; ++m) { const int row = row0 + ai * HALF + m * 16;
; #pragma unroll
;                 for (int bj = 0; bj < 2; ++bj) { const int col = col0 + bj * HALF;
;                     if (u.split) { float* pp = part + ((size_t)(u.k0 / u.nt) * (MROWS - MP) + (size_t)(row - MP)) * 2048 + col;
;                         *(f32x4*)pp = g[bj][0] * acc[ai][bj][m][0]; *(f32x4*)(pp + 4) = g[bj][1] * acc[ai][bj][m][1];
;                     } else {
;                         f32x4 b0, b1;
;                         if (xp) { const float* src = xp + (size_t)row * 2048 + col; b0 = *(const f32x4*)src; b1 = *(const f32x4*)(src + 4); }
.LBB0_541:
	s_nop 0
	v_or_b32_e32 v128, 16, v168
	v_ashrrev_i32_e32 v129, 31, v128
	v_lshlrev_b64 v[140:141], 13, v[128:129]
	s_andn2_b64 vcc, exec, s[60:61]
	v_lshlrev_b64 v[136:137], 12, v[128:129]
	s_cbranch_vccnz .LBB0_546
	s_andn2_b64 vcc, exec, s[22:23]
	s_cbranch_vccnz .LBB0_649
	v_lshl_add_u64 v[128:129], s[36:37], 0, v[140:141]
	v_lshl_add_u64 v[128:129], v[166:167], 2, v[128:129]
	s_nop 0
	s_nop 0
	s_nop 0
	s_cbranch_execnz .LBB0_545

; __device__ __forceinline__ u32x4 pack8(f32x4 v0, f32x4 v1) { u32x4 w; w.x = cvt_pk_bf16(v0[0], v0[1]); w.y = cvt_pk_bf16(v0[2], v0[3]); w.z = cvt_pk_bf16(v1[0], v1[1]); w.w = cvt_pk_bf16(v1[2], v1[3]); return w; }
;     __device__ __forceinline__ void operator()(const f32x4 (&acc)[2][2][4][2], const Unit& u, int wr, int wc, int fr, int fq) const {
;     ...
;                 for (int bj = 0; bj < 2; ++bj) { const int col = col0 + bj * HALF;
;                     if (u.split) { float* pp = part + ((size_t)(u.k0 / u.nt) * (MROWS - MP) + (size_t)(row - MP)) * 2048 + col;
;                         *(f32x4*)pp = g[bj][0] * acc[ai][bj][m][0]; *(f32x4*)(pp + 4) = g[bj][1] * acc[ai][bj][m][1];
;                     } else {
;                         f32x4 b0, b1;
;                         if (xp) { const float* src = xp + (size_t)row * 2048 + col; b0 = *(const f32x4*)src; b1 = *(const f32x4*)(src + 4); }
;                         else { const u32x4 w = *(const u32x4*)(baseb + (size_t)row * 2048 + col);
;                             b0 = (f32x4){__builtin_bit_cast(float, w.x << 16), __builtin_bit_cast(float, w.x & 0xffff0000u), __builtin_bit_cast(float, w.y << 16), __builtin_bit_cast(float, w.y & 0xffff0000u)};
;                             b1 = (f32x4){__builtin_bit_cast(float, w.z << 16), __builtin_bit_cast(float, w.z & 0xffff0000u), __builtin_bit_cast(float, w.w << 16), __builtin_bit_cast(float, w.w & 0xffff0000u)}; }
;                         *(u32x4*)(outb + (size_t)row * 2048 + col) = pack8(b0 + g[bj][0] * acc[ai][bj][m][0], b1 + g[bj][1] * acc[ai][bj][m][1]); } } }
.LBB0_545:
	s_waitcnt vmcnt(12)
	v_pk_fma_f32 v[120:121], v[120:121], v[124:125], v[204:205]
	v_pk_fma_f32 v[128:129], v[114:115], v[118:119], v[202:203]
	v_pk_fma_f32 v[114:115], v[112:113], v[116:117], v[200:201]
	v_cvt_pk_bf16_f32 v112, v120, v121
	v_lshl_add_u64 v[120:121], s[12:13], 0, v[136:137]
	v_lshl_add_u64 v[120:121], v[166:167], 1, v[120:121]
	v_pk_fma_f32 v[122:123], v[122:123], v[126:127], v[206:207]
	s_nop 0
	v_cvt_pk_bf16_f32 v113, v122, v123
	v_cvt_pk_bf16_f32 v114, v114, v115
	v_cvt_pk_bf16_f32 v115, v128, v129
	global_store_dwordx4 v[120:121], v[112:115], off

;     __device__ __forceinline__ void operator()(const f32x4 (&acc)[2][2][4][2], const Unit& u, int wr, int wc, int fr, int fq) const {
;     ...
;             for (int m = 0; m < 4; ++m) { const int row = row0 + ai * HALF + m * 16;
; #pragma unroll
;                 for (int bj = 0; bj < 2; ++bj) { const int col = col0 + bj * HALF;
;                     if (u.split) { float* pp = part + ((size_t)(u.k0 / u.nt) * (MROWS - MP) + (size_t)(row - MP)) * 2048 + col;
;                         *(f32x4*)pp = g[bj][0] * acc[ai][bj][m][0]; *(f32x4*)(pp + 4) = g[bj][1] * acc[ai][bj][m][1];
;                     } else {
;                         f32x4 b0, b1;
;                         if (xp) { const float* src = xp + (size_t)row * 2048 + col; b0 = *(const f32x4*)src; b1 = *(const f32x4*)(src + 4); }
.LBB0_550:
.LBB0_551:
	s_andn2_b64 vcc, exec, s[22:23]
	s_cbranch_vccnz .LBB0_650
	v_lshl_add_u64 v[112:113], s[36:37], 0, v[140:141]
	v_lshl_add_u64 v[112:113], v[166:167], 2, v[112:113]
	s_nop 0
	s_nop 0
	s_nop 0
	s_cbranch_execnz .LBB0_554

; __device__ __forceinline__ u32x4 pack8(f32x4 v0, f32x4 v1) { u32x4 w; w.x = cvt_pk_bf16(v0[0], v0[1]); w.y = cvt_pk_bf16(v0[2], v0[3]); w.z = cvt_pk_bf16(v1[0], v1[1]); w.w = cvt_pk_bf16(v1[2], v1[3]); return w; }
;     __device__ __forceinline__ void operator()(const f32x4 (&acc)[2][2][4][2], const Unit& u, int wr, int wc, int fr, int fq) const {
;     ...
;                 for (int bj = 0; bj < 2; ++bj) { const int col = col0 + bj * HALF;
;                     if (u.split) { float* pp = part + ((size_t)(u.k0 / u.nt) * (MROWS - MP) + (size_t)(row - MP)) * 2048 + col;
;                         *(f32x4*)pp = g[bj][0] * acc[ai][bj][m][0]; *(f32x4*)(pp + 4) = g[bj][1] * acc[ai][bj][m][1];
;                     } else {
;                         f32x4 b0, b1;
;                         if (xp) { const float* src = xp + (size_t)row * 2048 + col; b0 = *(const f32x4*)src; b1 = *(const f32x4*)(src + 4); }
;                         else { const u32x4 w = *(const u32x4*)(baseb + (size_t)row * 2048 + col);
;                             b0 = (f32x4){__builtin_bit_cast(float, w.x << 16), __builtin_bit_cast(float, w.x & 0xffff0000u), __builtin_bit_cast(float, w.y << 16), __builtin_bit_cast(float, w.y & 0xffff0000u)};
;                             b1 = (f32x4){__builtin_bit_cast(float, w.z << 16), __builtin_bit_cast(float, w.z & 0xffff0000u), __builtin_bit_cast(float, w.w << 16), __builtin_bit_cast(float, w.w & 0xffff0000u)}; }
;                         *(u32x4*)(outb + (size_t)row * 2048 + col) = pack8(b0 + g[bj][0] * acc[ai][bj][m][0], b1 + g[bj][1] * acc[ai][bj][m][1]); } } }
.LBB0_554:
	s_waitcnt vmcnt(11)
	v_pk_fma_f32 v[100:101], v[100:101], v[108:109], v[212:213]
	v_pk_fma_f32 v[112:113], v[98:99], v[106:107], v[210:211]
	v_pk_fma_f32 v[98:99], v[96:97], v[104:105], v[208:209]
	v_cvt_pk_bf16_f32 v96, v100, v101
	v_lshl_add_u64 v[100:101], s[12:13], 0, v[136:137]
	v_lshl_add_u64 v[100:101], v[166:167], 1, v[100:101]
	v_pk_fma_f32 v[102:103], v[102:103], v[110:111], v[214:215]
	s_nop 0
	v_cvt_pk_bf16_f32 v97, v102, v103
	v_cvt_pk_bf16_f32 v98, v98, v99
	v_cvt_pk_bf16_f32 v99, v112, v113
	global_store_dwordx4 v[100:101], v[96:99], off offset:256
	s_nop 1
	v_lshlrev_b64 v[96:97], 13, v[168:169]
	s_and_b64 vcc, exec, s[4:5]
	v_lshl_add_u64 v[114:115], v[96:97], 0, s[28:29]
	s_cbranch_vccz .LBB0_549

;     __device__ __forceinline__ void operator()(const f32x4 (&acc)[2][2][4][2], const Unit& u, int wr, int wc, int fr, int fq) const {
;     ...
;             for (int m = 0; m < 4; ++m) { const int row = row0 + ai * HALF + m * 16;
; #pragma unroll
;                 for (int bj = 0; bj < 2; ++bj) { const int col = col0 + bj * HALF;
;                     if (u.split) { float* pp = part + ((size_t)(u.k0 / u.nt) * (MROWS - MP) + (size_t)(row - MP)) * 2048 + col;
;                         *(f32x4*)pp = g[bj][0] * acc[ai][bj][m][0]; *(f32x4*)(pp + 4) = g[bj][1] * acc[ai][bj][m][1];
;                     } else {
;                         f32x4 b0, b1;
;                         if (xp) { const float* src = xp + (size_t)row * 2048 + col; b0 = *(const f32x4*)src; b1 = *(const f32x4*)(src + 4); }
.LBB0_556:
	s_nop 0
	v_or_b32_e32 v96, 32, v168
	v_ashrrev_i32_e32 v97, 31, v96
	v_lshlrev_b64 v[120:121], 13, v[96:97]
	s_andn2_b64 vcc, exec, s[60:61]
	v_lshlrev_b64 v[112:113], 12, v[96:97]
	s_cbranch_vccnz .LBB0_561
	s_andn2_b64 vcc, exec, s[22:23]
	s_cbranch_vccnz .LBB0_651
	v_lshl_add_u64 v[96:97], s[36:37], 0, v[120:121]
	v_lshl_add_u64 v[96:97], v[166:167], 2, v[96:97]
	s_nop 0
	s_nop 0
	s_nop 0
	s_cbranch_execnz .LBB0_560

; __device__ __forceinline__ u32x4 pack8(f32x4 v0, f32x4 v1) { u32x4 w; w.x = cvt_pk_bf16(v0[0], v0[1]); w.y = cvt_pk_bf16(v0[2], v0[3]); w.z = cvt_pk_bf16(v1[0], v1[1]); w.w = cvt_pk_bf16(v1[2], v1[3]); return w; }
;     __device__ __forceinline__ void operator()(const f32x4 (&acc)[2][2][4][2], const Unit& u, int wr, int wc, int fr, int fq) const {
;     ...
;                 for (int bj = 0; bj < 2; ++bj) { const int col = col0 + bj * HALF;
;                     if (u.split) { float* pp = part + ((size_t)(u.k0 / u.nt) * (MROWS - MP) + (size_t)(row - MP)) * 2048 + col;
;                         *(f32x4*)pp = g[bj][0] * acc[ai][bj][m][0]; *(f32x4*)(pp + 4) = g[bj][1] * acc[ai][bj][m][1];
;                     } else {
;                         f32x4 b0, b1;
;                         if (xp) { const float* src = xp + (size_t)row * 2048 + col; b0 = *(const f32x4*)src; b1 = *(const f32x4*)(src + 4); }
;                         else { const u32x4 w = *(const u32x4*)(baseb + (size_t)row * 2048 + col);
;                             b0 = (f32x4){__builtin_bit_cast(float, w.x << 16), __builtin_bit_cast(float, w.x & 0xffff0000u), __builtin_bit_cast(float, w.y << 16), __builtin_bit_cast(float, w.y & 0xffff0000u)};
;                             b1 = (f32x4){__builtin_bit_cast(float, w.z << 16), __builtin_bit_cast(float, w.z & 0xffff0000u), __builtin_bit_cast(float, w.w << 16), __builtin_bit_cast(float, w.w & 0xffff0000u)}; }
;                         *(u32x4*)(outb + (size_t)row * 2048 + col) = pack8(b0 + g[bj][0] * acc[ai][bj][m][0], b1 + g[bj][1] * acc[ai][bj][m][1]); } } }
.LBB0_560:
	s_waitcnt vmcnt(10)
	v_pk_fma_f32 v[92:93], v[92:93], v[124:125], v[220:221]
	v_pk_fma_f32 v[96:97], v[90:91], v[118:119], v[218:219]
	v_pk_fma_f32 v[90:91], v[88:89], v[116:117], v[216:217]
	v_cvt_pk_bf16_f32 v88, v92, v93
	v_lshl_add_u64 v[92:93], s[12:13], 0, v[112:113]
	v_lshl_add_u64 v[92:93], v[166:167], 1, v[92:93]
	v_pk_fma_f32 v[94:95], v[94:95], v[126:127], v[222:223]
	s_nop 0
	v_cvt_pk_bf16_f32 v89, v94, v95
	v_cvt_pk_bf16_f32 v90, v90, v91
	v_cvt_pk_bf16_f32 v91, v96, v97
	global_store_dwordx4 v[92:93], v[88:91], off

;     __device__ __forceinline__ void operator()(const f32x4 (&acc)[2][2][4][2], const Unit& u, int wr, int wc, int fr, int fq) const {
;     ...
;             for (int m = 0; m < 4; ++m) { const int row = row0 + ai * HALF + m * 16;
; #pragma unroll
;                 for (int bj = 0; bj < 2; ++bj) { const int col = col0 + bj * HALF;
;                     if (u.split) { float* pp = part + ((size_t)(u.k0 / u.nt) * (MROWS - MP) + (size_t)(row - MP)) * 2048 + col;
;                         *(f32x4*)pp = g[bj][0] * acc[ai][bj][m][0]; *(f32x4*)(pp + 4) = g[bj][1] * acc[ai][bj][m][1];
;                     } else {
;                         f32x4 b0, b1;
;                         if (xp) { const float* src = xp + (size_t)row * 2048 + col; b0 = *(const f32x4*)src; b1 = *(const f32x4*)(src + 4); }
.LBB0_565:
.LBB0_566:
	s_andn2_b64 vcc, exec, s[22:23]
	s_cbranch_vccnz .LBB0_652
	v_lshl_add_u64 v[88:89], s[36:37], 0, v[120:121]
	v_lshl_add_u64 v[88:89], v[166:167], 2, v[88:89]
	s_nop 0
	s_nop 0
	s_nop 0
	s_cbranch_execnz .LBB0_569

; __device__ __forceinline__ u32x4 pack8(f32x4 v0, f32x4 v1) { u32x4 w; w.x = cvt_pk_bf16(v0[0], v0[1]); w.y = cvt_pk_bf16(v0[2], v0[3]); w.z = cvt_pk_bf16(v1[0], v1[1]); w.w = cvt_pk_bf16(v1[2], v1[3]); return w; }
;     __device__ __forceinline__ void operator()(const f32x4 (&acc)[2][2][4][2], const Unit& u, int wr, int wc, int fr, int fq) const {
;     ...
;                 for (int bj = 0; bj < 2; ++bj) { const int col = col0 + bj * HALF;
;                     if (u.split) { float* pp = part + ((size_t)(u.k0 / u.nt) * (MROWS - MP) + (size_t)(row - MP)) * 2048 + col;
;                         *(f32x4*)pp = g[bj][0] * acc[ai][bj][m][0]; *(f32x4*)(pp + 4) = g[bj][1] * acc[ai][bj][m][1];
;                     } else {
;                         f32x4 b0, b1;
;                         if (xp) { const float* src = xp + (size_t)row * 2048 + col; b0 = *(const f32x4*)src; b1 = *(const f32x4*)(src + 4); }
;                         else { const u32x4 w = *(const u32x4*)(baseb + (size_t)row * 2048 + col);
;                             b0 = (f32x4){__builtin_bit_cast(float, w.x << 16), __builtin_bit_cast(float, w.x & 0xffff0000u), __builtin_bit_cast(float, w.y << 16), __builtin_bit_cast(float, w.y & 0xffff0000u)};
;                             b1 = (f32x4){__builtin_bit_cast(float, w.z << 16), __builtin_bit_cast(float, w.z & 0xffff0000u), __builtin_bit_cast(float, w.w << 16), __builtin_bit_cast(float, w.w & 0xffff0000u)}; }
;                         *(u32x4*)(outb + (size_t)row * 2048 + col) = pack8(b0 + g[bj][0] * acc[ai][bj][m][0], b1 + g[bj][1] * acc[ai][bj][m][1]); } } }
.LBB0_569:
	s_waitcnt vmcnt(9)
	v_pk_fma_f32 v[84:85], v[84:85], v[108:109], v[228:229]
	v_pk_fma_f32 v[88:89], v[82:83], v[106:107], v[226:227]
	v_pk_fma_f32 v[82:83], v[80:81], v[104:105], v[224:225]
	v_cvt_pk_bf16_f32 v80, v84, v85
	v_lshl_add_u64 v[84:85], s[12:13], 0, v[112:113]
	v_lshl_add_u64 v[84:85], v[166:167], 1, v[84:85]
	v_pk_fma_f32 v[86:87], v[86:87], v[110:111], v[230:231]
	s_nop 0
	v_cvt_pk_bf16_f32 v81, v86, v87
	v_cvt_pk_bf16_f32 v82, v82, v83
	v_cvt_pk_bf16_f32 v83, v88, v89
	global_store_dwordx4 v[84:85], v[80:83], off offset:256
	s_nop 1
	v_lshlrev_b64 v[80:81], 13, v[168:169]
	s_and_b64 vcc, exec, s[4:5]
	v_lshl_add_u64 v[90:91], v[80:81], 0, s[40:41]
	s_cbranch_vccz .LBB0_564

;     __device__ __forceinline__ void operator()(const f32x4 (&acc)[2][2][4][2], const Unit& u, int wr, int wc, int fr, int fq) const {
;     ...
;             for (int m = 0; m < 4; ++m) { const int row = row0 + ai * HALF + m * 16;
; #pragma unroll
;                 for (int bj = 0; bj < 2; ++bj) { const int col = col0 + bj * HALF;
;                     if (u.split) { float* pp = part + ((size_t)(u.k0 / u.nt) * (MROWS - MP) + (size_t)(row - MP)) * 2048 + col;
;                         *(f32x4*)pp = g[bj][0] * acc[ai][bj][m][0]; *(f32x4*)(pp + 4) = g[bj][1] * acc[ai][bj][m][1];
;                     } else {
;                         f32x4 b0, b1;
;                         if (xp) { const float* src = xp + (size_t)row * 2048 + col; b0 = *(const f32x4*)src; b1 = *(const f32x4*)(src + 4); }
.LBB0_571:
	s_nop 0
	v_or_b32_e32 v80, 48, v168
	v_ashrrev_i32_e32 v81, 31, v80
	v_lshlrev_b64 v[92:93], 13, v[80:81]
	s_andn2_b64 vcc, exec, s[60:61]
	v_lshlrev_b64 v[88:89], 12, v[80:81]
	s_cbranch_vccnz .LBB0_576
	s_andn2_b64 vcc, exec, s[22:23]
	s_cbranch_vccnz .LBB0_653
	v_lshl_add_u64 v[80:81], s[36:37], 0, v[92:93]
	v_lshl_add_u64 v[80:81], v[166:167], 2, v[80:81]
	s_nop 0
	s_nop 0
	s_nop 0
	s_cbranch_execnz .LBB0_575

; __device__ __forceinline__ u32x4 pack8(f32x4 v0, f32x4 v1) { u32x4 w; w.x = cvt_pk_bf16(v0[0], v0[1]); w.y = cvt_pk_bf16(v0[2], v0[3]); w.z = cvt_pk_bf16(v1[0], v1[1]); w.w = cvt_pk_bf16(v1[2], v1[3]); return w; }
;     __device__ __forceinline__ void operator()(const f32x4 (&acc)[2][2][4][2], const Unit& u, int wr, int wc, int fr, int fq) const {
;     ...
;                 for (int bj = 0; bj < 2; ++bj) { const int col = col0 + bj * HALF;
;                     if (u.split) { float* pp = part + ((size_t)(u.k0 / u.nt) * (MROWS - MP) + (size_t)(row - MP)) * 2048 + col;
;                         *(f32x4*)pp = g[bj][0] * acc[ai][bj][m][0]; *(f32x4*)(pp + 4) = g[bj][1] * acc[ai][bj][m][1];
;                     } else {
;                         f32x4 b0, b1;
;                         if (xp) { const float* src = xp + (size_t)row * 2048 + col; b0 = *(const f32x4*)src; b1 = *(const f32x4*)(src + 4); }
;                         else { const u32x4 w = *(const u32x4*)(baseb + (size_t)row * 2048 + col);
;                             b0 = (f32x4){__builtin_bit_cast(float, w.x << 16), __builtin_bit_cast(float, w.x & 0xffff0000u), __builtin_bit_cast(float, w.y << 16), __builtin_bit_cast(float, w.y & 0xffff0000u)};
;                             b1 = (f32x4){__builtin_bit_cast(float, w.z << 16), __builtin_bit_cast(float, w.z & 0xffff0000u), __builtin_bit_cast(float, w.w << 16), __builtin_bit_cast(float, w.w & 0xffff0000u)}; }
;                         *(u32x4*)(outb + (size_t)row * 2048 + col) = pack8(b0 + g[bj][0] * acc[ai][bj][m][0], b1 + g[bj][1] * acc[ai][bj][m][1]); } } }
.LBB0_575:
	s_waitcnt vmcnt(8)
	v_pk_fma_f32 v[76:77], v[76:77], v[124:125], v[236:237]
	v_pk_fma_f32 v[80:81], v[74:75], v[118:119], v[234:235]
	v_pk_fma_f32 v[74:75], v[72:73], v[116:117], v[232:233]
	v_cvt_pk_bf16_f32 v72, v76, v77
	v_lshl_add_u64 v[76:77], s[12:13], 0, v[88:89]
	v_lshl_add_u64 v[76:77], v[166:167], 1, v[76:77]
	v_pk_fma_f32 v[78:79], v[78:79], v[126:127], v[238:239]
	s_nop 0
	v_cvt_pk_bf16_f32 v73, v78, v79
	v_cvt_pk_bf16_f32 v74, v74, v75
	v_cvt_pk_bf16_f32 v75, v80, v81
	global_store_dwordx4 v[76:77], v[72:75], off

;     __device__ __forceinline__ void operator()(const f32x4 (&acc)[2][2][4][2], const Unit& u, int wr, int wc, int fr, int fq) const {
;     ...
;             for (int m = 0; m < 4; ++m) { const int row = row0 + ai * HALF + m * 16;
; #pragma unroll
;                 for (int bj = 0; bj < 2; ++bj) { const int col = col0 + bj * HALF;
;                     if (u.split) { float* pp = part + ((size_t)(u.k0 / u.nt) * (MROWS - MP) + (size_t)(row - MP)) * 2048 + col;
;                         *(f32x4*)pp = g[bj][0] * acc[ai][bj][m][0]; *(f32x4*)(pp + 4) = g[bj][1] * acc[ai][bj][m][1];
;                     } else {
;                         f32x4 b0, b1;
;                         if (xp) { const float* src = xp + (size_t)row * 2048 + col; b0 = *(const f32x4*)src; b1 = *(const f32x4*)(src + 4); }
.LBB0_578:
.LBB0_579:
	s_andn2_b64 vcc, exec, s[22:23]
	s_cbranch_vccnz .LBB0_654
	v_lshl_add_u64 v[72:73], s[36:37], 0, v[92:93]
	v_lshl_add_u64 v[72:73], v[166:167], 2, v[72:73]
	s_nop 0
	s_nop 0
	s_nop 0
	s_cbranch_execnz .LBB0_582

; __device__ __forceinline__ u32x4 pack8(f32x4 v0, f32x4 v1) { u32x4 w; w.x = cvt_pk_bf16(v0[0], v0[1]); w.y = cvt_pk_bf16(v0[2], v0[3]); w.z = cvt_pk_bf16(v1[0], v1[1]); w.w = cvt_pk_bf16(v1[2], v1[3]); return w; }
;     __device__ __forceinline__ void operator()(const f32x4 (&acc)[2][2][4][2], const Unit& u, int wr, int wc, int fr, int fq) const {
;     ...
;                 for (int bj = 0; bj < 2; ++bj) { const int col = col0 + bj * HALF;
;                     if (u.split) { float* pp = part + ((size_t)(u.k0 / u.nt) * (MROWS - MP) + (size_t)(row - MP)) * 2048 + col;
;                         *(f32x4*)pp = g[bj][0] * acc[ai][bj][m][0]; *(f32x4*)(pp + 4) = g[bj][1] * acc[ai][bj][m][1];
;                     } else {
;                         f32x4 b0, b1;
;                         if (xp) { const float* src = xp + (size_t)row * 2048 + col; b0 = *(const f32x4*)src; b1 = *(const f32x4*)(src + 4); }
;                         else { const u32x4 w = *(const u32x4*)(baseb + (size_t)row * 2048 + col);
;                             b0 = (f32x4){__builtin_bit_cast(float, w.x << 16), __builtin_bit_cast(float, w.x & 0xffff0000u), __builtin_bit_cast(float, w.y << 16), __builtin_bit_cast(float, w.y & 0xffff0000u)};
;                             b1 = (f32x4){__builtin_bit_cast(float, w.z << 16), __builtin_bit_cast(float, w.z & 0xffff0000u), __builtin_bit_cast(float, w.w << 16), __builtin_bit_cast(float, w.w & 0xffff0000u)}; }
;                         *(u32x4*)(outb + (size_t)row * 2048 + col) = pack8(b0 + g[bj][0] * acc[ai][bj][m][0], b1 + g[bj][1] * acc[ai][bj][m][1]); } } }
.LBB0_582:
	s_waitcnt vmcnt(7)
	v_pk_fma_f32 v[68:69], v[68:69], v[108:109], v[244:245]
	v_pk_fma_f32 v[72:73], v[66:67], v[106:107], v[242:243]
	v_pk_fma_f32 v[66:67], v[64:65], v[104:105], v[240:241]
	v_cvt_pk_bf16_f32 v64, v68, v69
	v_lshl_add_u64 v[68:69], s[12:13], 0, v[88:89]
	v_lshl_add_u64 v[68:69], v[166:167], 1, v[68:69]
	v_pk_fma_f32 v[70:71], v[70:71], v[110:111], v[246:247]
	s_nop 0
	v_cvt_pk_bf16_f32 v65, v70, v71
	v_cvt_pk_bf16_f32 v66, v66, v67
	v_cvt_pk_bf16_f32 v67, v72, v73
	global_store_dwordx4 v[68:69], v[64:67], off offset:256

;     __device__ __forceinline__ void operator()(const f32x4 (&acc)[2][2][4][2], const Unit& u, int wr, int wc, int fr, int fq) const {
;     ...
;             for (int m = 0; m < 4; ++m) { const int row = row0 + ai * HALF + m * 16;
; #pragma unroll
;                 for (int bj = 0; bj < 2; ++bj) { const int col = col0 + bj * HALF;
;                     if (u.split) { float* pp = part + ((size_t)(u.k0 / u.nt) * (MROWS - MP) + (size_t)(row - MP)) * 2048 + col;
;                         *(f32x4*)pp = g[bj][0] * acc[ai][bj][m][0]; *(f32x4*)(pp + 4) = g[bj][1] * acc[ai][bj][m][1];
;                     } else {
;                         f32x4 b0, b1;
;                         if (xp) { const float* src = xp + (size_t)row * 2048 + col; b0 = *(const f32x4*)src; b1 = *(const f32x4*)(src + 4); }
.LBB0_586:
	s_nop 0
	v_add_u32_e32 v80, 0x80, v168
	v_ashrrev_i32_e32 v81, 31, v80
	v_lshlrev_b64 v[92:93], 13, v[80:81]
	s_andn2_b64 vcc, exec, s[60:61]
	v_lshlrev_b64 v[88:89], 12, v[80:81]
	s_cbranch_vccnz .LBB0_591
	s_andn2_b64 vcc, exec, s[22:23]
	s_cbranch_vccnz .LBB0_655
	v_lshl_add_u64 v[248:249], s[36:37], 0, v[92:93]
	v_lshl_add_u64 v[248:249], v[166:167], 2, v[248:249]
	global_load_dwordx4 v[184:187], v[248:249], off offset:16
	global_load_dwordx4 v[188:191], v[248:249], off
	global_load_dwordx4 v[192:195], v[248:249], off offset:528
	global_load_dwordx4 v[196:199], v[248:249], off offset:512
	v_add_co_u32_e32 v248, vcc, 0x20000, v248
	s_nop 1
	v_addc_co_u32_e32 v249, vcc, 0, v249, vcc
	global_load_dwordx4 v[200:203], v[248:249], off offset:16
	global_load_dwordx4 v[204:207], v[248:249], off
	global_load_dwordx4 v[208:211], v[248:249], off offset:528
	global_load_dwordx4 v[212:215], v[248:249], off offset:512
	v_add_co_u32_e32 v248, vcc, 0x20000, v248
	s_nop 1
	v_addc_co_u32_e32 v249, vcc, 0, v249, vcc
	global_load_dwordx4 v[216:219], v[248:249], off offset:16
	global_load_dwordx4 v[220:223], v[248:249], off
	global_load_dwordx4 v[224:227], v[248:249], off offset:528
	global_load_dwordx4 v[228:231], v[248:249], off offset:512
	v_add_co_u32_e32 v248, vcc, 0x20000, v248
	s_nop 1
	v_addc_co_u32_e32 v249, vcc, 0, v249, vcc
	global_load_dwordx4 v[232:235], v[248:249], off offset:16
	global_load_dwordx4 v[236:239], v[248:249], off
	global_load_dwordx4 v[240:243], v[248:249], off offset:528
	global_load_dwordx4 v[244:247], v[248:249], off offset:512
	v_lshl_add_u64 v[80:81], s[36:37], 0, v[92:93]
	v_lshl_add_u64 v[80:81], v[166:167], 2, v[80:81]
	s_nop 0
	s_nop 0
	s_nop 0
	s_cbranch_execnz .LBB0_590

; __device__ __forceinline__ u32x4 pack8(f32x4 v0, f32x4 v1) { u32x4 w; w.x = cvt_pk_bf16(v0[0], v0[1]); w.y = cvt_pk_bf16(v0[2], v0[3]); w.z = cvt_pk_bf16(v1[0], v1[1]); w.w = cvt_pk_bf16(v1[2], v1[3]); return w; }
;     __device__ __forceinline__ void operator()(const f32x4 (&acc)[2][2][4][2], const Unit& u, int wr, int wc, int fr, int fq) const {
;     ...
;                 for (int bj = 0; bj < 2; ++bj) { const int col = col0 + bj * HALF;
;                     if (u.split) { float* pp = part + ((size_t)(u.k0 / u.nt) * (MROWS - MP) + (size_t)(row - MP)) * 2048 + col;
;                         *(f32x4*)pp = g[bj][0] * acc[ai][bj][m][0]; *(f32x4*)(pp + 4) = g[bj][1] * acc[ai][bj][m][1];
;                     } else {
;                         f32x4 b0, b1;
;                         if (xp) { const float* src = xp + (size_t)row * 2048 + col; b0 = *(const f32x4*)src; b1 = *(const f32x4*)(src + 4); }
;                         else { const u32x4 w = *(const u32x4*)(baseb + (size_t)row * 2048 + col);
;                             b0 = (f32x4){__builtin_bit_cast(float, w.x << 16), __builtin_bit_cast(float, w.x & 0xffff0000u), __builtin_bit_cast(float, w.y << 16), __builtin_bit_cast(float, w.y & 0xffff0000u)};
;                             b1 = (f32x4){__builtin_bit_cast(float, w.z << 16), __builtin_bit_cast(float, w.z & 0xffff0000u), __builtin_bit_cast(float, w.w << 16), __builtin_bit_cast(float, w.w & 0xffff0000u)}; }
;                         *(u32x4*)(outb + (size_t)row * 2048 + col) = pack8(b0 + g[bj][0] * acc[ai][bj][m][0], b1 + g[bj][1] * acc[ai][bj][m][1]); } } }
.LBB0_590:
	s_waitcnt vmcnt(14)
	v_pk_fma_f32 v[60:61], v[60:61], v[76:77], v[188:189]
	v_pk_fma_f32 v[80:81], v[58:59], v[74:75], v[186:187]
	v_pk_fma_f32 v[58:59], v[56:57], v[72:73], v[184:185]
	v_cvt_pk_bf16_f32 v56, v60, v61
	v_lshl_add_u64 v[60:61], s[12:13], 0, v[88:89]
	v_lshl_add_u64 v[60:61], v[166:167], 1, v[60:61]
	v_pk_fma_f32 v[62:63], v[62:63], v[78:79], v[190:191]
	s_nop 0
	v_cvt_pk_bf16_f32 v57, v62, v63
	v_cvt_pk_bf16_f32 v58, v58, v59
	v_cvt_pk_bf16_f32 v59, v80, v81
	global_store_dwordx4 v[60:61], v[56:59], off

;     __device__ __forceinline__ void operator()(const f32x4 (&acc)[2][2][4][2], const Unit& u, int wr, int wc, int fr, int fq) const {
;     ...
;             for (int m = 0; m < 4; ++m) { const int row = row0 + ai * HALF + m * 16;
; #pragma unroll
;                 for (int bj = 0; bj < 2; ++bj) { const int col = col0 + bj * HALF;
;                     if (u.split) { float* pp = part + ((size_t)(u.k0 / u.nt) * (MROWS - MP) + (size_t)(row - MP)) * 2048 + col;
;                         *(f32x4*)pp = g[bj][0] * acc[ai][bj][m][0]; *(f32x4*)(pp + 4) = g[bj][1] * acc[ai][bj][m][1];
;                     } else {
;                         f32x4 b0, b1;
;                         if (xp) { const float* src = xp + (size_t)row * 2048 + col; b0 = *(const f32x4*)src; b1 = *(const f32x4*)(src + 4); }
.LBB0_595:
.LBB0_596:
	s_andn2_b64 vcc, exec, s[22:23]
	s_cbranch_vccnz .LBB0_656
	v_lshl_add_u64 v[56:57], s[36:37], 0, v[92:93]
	v_lshl_add_u64 v[56:57], v[166:167], 2, v[56:57]
	s_nop 0
	s_nop 0
	s_nop 0
	s_cbranch_execnz .LBB0_599

; __device__ __forceinline__ u32x4 pack8(f32x4 v0, f32x4 v1) { u32x4 w; w.x = cvt_pk_bf16(v0[0], v0[1]); w.y = cvt_pk_bf16(v0[2], v0[3]); w.z = cvt_pk_bf16(v1[0], v1[1]); w.w = cvt_pk_bf16(v1[2], v1[3]); return w; }
;     __device__ __forceinline__ void operator()(const f32x4 (&acc)[2][2][4][2], const Unit& u, int wr, int wc, int fr, int fq) const {
;     ...
;                 for (int bj = 0; bj < 2; ++bj) { const int col = col0 + bj * HALF;
;                     if (u.split) { float* pp = part + ((size_t)(u.k0 / u.nt) * (MROWS - MP) + (size_t)(row - MP)) * 2048 + col;
;                         *(f32x4*)pp = g[bj][0] * acc[ai][bj][m][0]; *(f32x4*)(pp + 4) = g[bj][1] * acc[ai][bj][m][1];
;                     } else {
;                         f32x4 b0, b1;
;                         if (xp) { const float* src = xp + (size_t)row * 2048 + col; b0 = *(const f32x4*)src; b1 = *(const f32x4*)(src + 4); }
;                         else { const u32x4 w = *(const u32x4*)(baseb + (size_t)row * 2048 + col);
;                             b0 = (f32x4){__builtin_bit_cast(float, w.x << 16), __builtin_bit_cast(float, w.x & 0xffff0000u), __builtin_bit_cast(float, w.y << 16), __builtin_bit_cast(float, w.y & 0xffff0000u)};
;                             b1 = (f32x4){__builtin_bit_cast(float, w.z << 16), __builtin_bit_cast(float, w.z & 0xffff0000u), __builtin_bit_cast(float, w.w << 16), __builtin_bit_cast(float, w.w & 0xffff0000u)}; }
;                         *(u32x4*)(outb + (size_t)row * 2048 + col) = pack8(b0 + g[bj][0] * acc[ai][bj][m][0], b1 + g[bj][1] * acc[ai][bj][m][1]); } } }
.LBB0_599:
	s_waitcnt vmcnt(13)
	v_pk_fma_f32 v[52:53], v[52:53], v[68:69], v[196:197]
	v_pk_fma_f32 v[56:57], v[50:51], v[66:67], v[194:195]
	v_pk_fma_f32 v[50:51], v[48:49], v[64:65], v[192:193]
	v_cvt_pk_bf16_f32 v48, v52, v53
	v_lshl_add_u64 v[52:53], s[12:13], 0, v[88:89]
	v_lshl_add_u64 v[52:53], v[166:167], 1, v[52:53]
	v_pk_fma_f32 v[54:55], v[54:55], v[70:71], v[198:199]
	s_nop 0
	v_cvt_pk_bf16_f32 v49, v54, v55
	v_cvt_pk_bf16_f32 v50, v50, v51
	v_cvt_pk_bf16_f32 v51, v56, v57
	global_store_dwordx4 v[52:53], v[48:51], off offset:256
	s_nop 1
	v_lshlrev_b64 v[48:49], 13, v[168:169]
	s_and_b64 vcc, exec, s[4:5]
	v_lshl_add_u64 v[58:59], v[48:49], 0, s[44:45]
	s_cbranch_vccz .LBB0_594

;     __device__ __forceinline__ void operator()(const f32x4 (&acc)[2][2][4][2], const Unit& u, int wr, int wc, int fr, int fq) const {
;     ...
;             for (int m = 0; m < 4; ++m) { const int row = row0 + ai * HALF + m * 16;
; #pragma unroll
;                 for (int bj = 0; bj < 2; ++bj) { const int col = col0 + bj * HALF;
;                     if (u.split) { float* pp = part + ((size_t)(u.k0 / u.nt) * (MROWS - MP) + (size_t)(row - MP)) * 2048 + col;
;                         *(f32x4*)pp = g[bj][0] * acc[ai][bj][m][0]; *(f32x4*)(pp + 4) = g[bj][1] * acc[ai][bj][m][1];
;                     } else {
;                         f32x4 b0, b1;
;                         if (xp) { const float* src = xp + (size_t)row * 2048 + col; b0 = *(const f32x4*)src; b1 = *(const f32x4*)(src + 4); }
.LBB0_601:
	s_nop 0
	v_add_u32_e32 v48, 0x90, v168
	v_ashrrev_i32_e32 v49, 31, v48
	v_lshlrev_b64 v[60:61], 13, v[48:49]
	s_andn2_b64 vcc, exec, s[60:61]
	v_lshlrev_b64 v[56:57], 12, v[48:49]
	s_cbranch_vccnz .LBB0_606
	s_andn2_b64 vcc, exec, s[22:23]
	s_cbranch_vccnz .LBB0_657
	v_lshl_add_u64 v[48:49], s[36:37], 0, v[60:61]
	v_lshl_add_u64 v[48:49], v[166:167], 2, v[48:49]
	s_nop 0
	s_nop 0
	s_nop 0
	s_cbranch_execnz .LBB0_605

; __device__ __forceinline__ u32x4 pack8(f32x4 v0, f32x4 v1) { u32x4 w; w.x = cvt_pk_bf16(v0[0], v0[1]); w.y = cvt_pk_bf16(v0[2], v0[3]); w.z = cvt_pk_bf16(v1[0], v1[1]); w.w = cvt_pk_bf16(v1[2], v1[3]); return w; }
;     __device__ __forceinline__ void operator()(const f32x4 (&acc)[2][2][4][2], const Unit& u, int wr, int wc, int fr, int fq) const {
;     ...
;                 for (int bj = 0; bj < 2; ++bj) { const int col = col0 + bj * HALF;
;                     if (u.split) { float* pp = part + ((size_t)(u.k0 / u.nt) * (MROWS - MP) + (size_t)(row - MP)) * 2048 + col;
;                         *(f32x4*)pp = g[bj][0] * acc[ai][bj][m][0]; *(f32x4*)(pp + 4) = g[bj][1] * acc[ai][bj][m][1];
;                     } else {
;                         f32x4 b0, b1;
;                         if (xp) { const float* src = xp + (size_t)row * 2048 + col; b0 = *(const f32x4*)src; b1 = *(const f32x4*)(src + 4); }
;                         else { const u32x4 w = *(const u32x4*)(baseb + (size_t)row * 2048 + col);
;                             b0 = (f32x4){__builtin_bit_cast(float, w.x << 16), __builtin_bit_cast(float, w.x & 0xffff0000u), __builtin_bit_cast(float, w.y << 16), __builtin_bit_cast(float, w.y & 0xffff0000u)};
;                             b1 = (f32x4){__builtin_bit_cast(float, w.z << 16), __builtin_bit_cast(float, w.z & 0xffff0000u), __builtin_bit_cast(float, w.w << 16), __builtin_bit_cast(float, w.w & 0xffff0000u)}; }
;                         *(u32x4*)(outb + (size_t)row * 2048 + col) = pack8(b0 + g[bj][0] * acc[ai][bj][m][0], b1 + g[bj][1] * acc[ai][bj][m][1]); } } }
.LBB0_605:
	s_waitcnt vmcnt(12)
	v_pk_fma_f32 v[44:45], v[44:45], v[76:77], v[204:205]
	v_pk_fma_f32 v[48:49], v[42:43], v[74:75], v[202:203]
	v_pk_fma_f32 v[42:43], v[40:41], v[72:73], v[200:201]
	v_cvt_pk_bf16_f32 v40, v44, v45
	v_lshl_add_u64 v[44:45], s[12:13], 0, v[56:57]
	v_lshl_add_u64 v[44:45], v[166:167], 1, v[44:45]
	v_pk_fma_f32 v[46:47], v[46:47], v[78:79], v[206:207]
	s_nop 0
	v_cvt_pk_bf16_f32 v41, v46, v47
	v_cvt_pk_bf16_f32 v42, v42, v43
	v_cvt_pk_bf16_f32 v43, v48, v49
	global_store_dwordx4 v[44:45], v[40:43], off

;     __device__ __forceinline__ void operator()(const f32x4 (&acc)[2][2][4][2], const Unit& u, int wr, int wc, int fr, int fq) const {
;     ...
;             for (int m = 0; m < 4; ++m) { const int row = row0 + ai * HALF + m * 16;
; #pragma unroll
;                 for (int bj = 0; bj < 2; ++bj) { const int col = col0 + bj * HALF;
;                     if (u.split) { float* pp = part + ((size_t)(u.k0 / u.nt) * (MROWS - MP) + (size_t)(row - MP)) * 2048 + col;
;                         *(f32x4*)pp = g[bj][0] * acc[ai][bj][m][0]; *(f32x4*)(pp + 4) = g[bj][1] * acc[ai][bj][m][1];
;                     } else {
;                         f32x4 b0, b1;
;                         if (xp) { const float* src = xp + (size_t)row * 2048 + col; b0 = *(const f32x4*)src; b1 = *(const f32x4*)(src + 4); }
.LBB0_610:
.LBB0_611:
	s_andn2_b64 vcc, exec, s[22:23]
	s_cbranch_vccnz .LBB0_658
	v_lshl_add_u64 v[40:41], s[36:37], 0, v[60:61]
	v_lshl_add_u64 v[40:41], v[166:167], 2, v[40:41]
	s_nop 0
	s_nop 0
	s_nop 0
	s_cbranch_execnz .LBB0_614

; __device__ __forceinline__ u32x4 pack8(f32x4 v0, f32x4 v1) { u32x4 w; w.x = cvt_pk_bf16(v0[0], v0[1]); w.y = cvt_pk_bf16(v0[2], v0[3]); w.z = cvt_pk_bf16(v1[0], v1[1]); w.w = cvt_pk_bf16(v1[2], v1[3]); return w; }
;     __device__ __forceinline__ void operator()(const f32x4 (&acc)[2][2][4][2], const Unit& u, int wr, int wc, int fr, int fq) const {
;     ...
;                 for (int bj = 0; bj < 2; ++bj) { const int col = col0 + bj * HALF;
;                     if (u.split) { float* pp = part + ((size_t)(u.k0 / u.nt) * (MROWS - MP) + (size_t)(row - MP)) * 2048 + col;
;                         *(f32x4*)pp = g[bj][0] * acc[ai][bj][m][0]; *(f32x4*)(pp + 4) = g[bj][1] * acc[ai][bj][m][1];
;                     } else {
;                         f32x4 b0, b1;
;                         if (xp) { const float* src = xp + (size_t)row * 2048 + col; b0 = *(const f32x4*)src; b1 = *(const f32x4*)(src + 4); }
;                         else { const u32x4 w = *(const u32x4*)(baseb + (size_t)row * 2048 + col);
;                             b0 = (f32x4){__builtin_bit_cast(float, w.x << 16), __builtin_bit_cast(float, w.x & 0xffff0000u), __builtin_bit_cast(float, w.y << 16), __builtin_bit_cast(float, w.y & 0xffff0000u)};
;                             b1 = (f32x4){__builtin_bit_cast(float, w.z << 16), __builtin_bit_cast(float, w.z & 0xffff0000u), __builtin_bit_cast(float, w.w << 16), __builtin_bit_cast(float, w.w & 0xffff0000u)}; }
;                         *(u32x4*)(outb + (size_t)row * 2048 + col) = pack8(b0 + g[bj][0] * acc[ai][bj][m][0], b1 + g[bj][1] * acc[ai][bj][m][1]); } } }
.LBB0_614:
	s_waitcnt vmcnt(11)
	v_pk_fma_f32 v[36:37], v[36:37], v[68:69], v[212:213]
	v_pk_fma_f32 v[40:41], v[34:35], v[66:67], v[210:211]
	v_pk_fma_f32 v[34:35], v[32:33], v[64:65], v[208:209]
	v_cvt_pk_bf16_f32 v32, v36, v37
	v_lshl_add_u64 v[36:37], s[12:13], 0, v[56:57]
	v_lshl_add_u64 v[36:37], v[166:167], 1, v[36:37]
	v_pk_fma_f32 v[38:39], v[38:39], v[70:71], v[214:215]
	s_nop 0
	v_cvt_pk_bf16_f32 v33, v38, v39
	v_cvt_pk_bf16_f32 v34, v34, v35
	v_cvt_pk_bf16_f32 v35, v40, v41
	global_store_dwordx4 v[36:37], v[32:35], off offset:256
	s_nop 1
	v_lshlrev_b64 v[32:33], 13, v[168:169]
	s_and_b64 vcc, exec, s[4:5]
	v_lshl_add_u64 v[42:43], v[32:33], 0, s[46:47]
	s_cbranch_vccz .LBB0_609

;     __device__ __forceinline__ void operator()(const f32x4 (&acc)[2][2][4][2], const Unit& u, int wr, int wc, int fr, int fq) const {
;     ...
;             for (int m = 0; m < 4; ++m) { const int row = row0 + ai * HALF + m * 16;
; #pragma unroll
;                 for (int bj = 0; bj < 2; ++bj) { const int col = col0 + bj * HALF;
;                     if (u.split) { float* pp = part + ((size_t)(u.k0 / u.nt) * (MROWS - MP) + (size_t)(row - MP)) * 2048 + col;
;                         *(f32x4*)pp = g[bj][0] * acc[ai][bj][m][0]; *(f32x4*)(pp + 4) = g[bj][1] * acc[ai][bj][m][1];
;                     } else {
;                         f32x4 b0, b1;
;                         if (xp) { const float* src = xp + (size_t)row * 2048 + col; b0 = *(const f32x4*)src; b1 = *(const f32x4*)(src + 4); }
.LBB0_616:
	s_nop 0
	v_add_u32_e32 v32, 0xa0, v168
	v_ashrrev_i32_e32 v33, 31, v32
	v_lshlrev_b64 v[44:45], 13, v[32:33]
	s_andn2_b64 vcc, exec, s[60:61]
	v_lshlrev_b64 v[40:41], 12, v[32:33]
	s_cbranch_vccnz .LBB0_621
	s_andn2_b64 vcc, exec, s[22:23]
	s_cbranch_vccnz .LBB0_659
	v_lshl_add_u64 v[32:33], s[36:37], 0, v[44:45]
	v_lshl_add_u64 v[32:33], v[166:167], 2, v[32:33]
	s_nop 0
	s_nop 0
	s_nop 0
	s_cbranch_execnz .LBB0_620

; __device__ __forceinline__ u32x4 pack8(f32x4 v0, f32x4 v1) { u32x4 w; w.x = cvt_pk_bf16(v0[0], v0[1]); w.y = cvt_pk_bf16(v0[2], v0[3]); w.z = cvt_pk_bf16(v1[0], v1[1]); w.w = cvt_pk_bf16(v1[2], v1[3]); return w; }
;     __device__ __forceinline__ void operator()(const f32x4 (&acc)[2][2][4][2], const Unit& u, int wr, int wc, int fr, int fq) const {
;     ...
;                 for (int bj = 0; bj < 2; ++bj) { const int col = col0 + bj * HALF;
;                     if (u.split) { float* pp = part + ((size_t)(u.k0 / u.nt) * (MROWS - MP) + (size_t)(row - MP)) * 2048 + col;
;                         *(f32x4*)pp = g[bj][0] * acc[ai][bj][m][0]; *(f32x4*)(pp + 4) = g[bj][1] * acc[ai][bj][m][1];
;                     } else {
;                         f32x4 b0, b1;
;                         if (xp) { const float* src = xp + (size_t)row * 2048 + col; b0 = *(const f32x4*)src; b1 = *(const f32x4*)(src + 4); }
;                         else { const u32x4 w = *(const u32x4*)(baseb + (size_t)row * 2048 + col);
;                             b0 = (f32x4){__builtin_bit_cast(float, w.x << 16), __builtin_bit_cast(float, w.x & 0xffff0000u), __builtin_bit_cast(float, w.y << 16), __builtin_bit_cast(float, w.y & 0xffff0000u)};
;                             b1 = (f32x4){__builtin_bit_cast(float, w.z << 16), __builtin_bit_cast(float, w.z & 0xffff0000u), __builtin_bit_cast(float, w.w << 16), __builtin_bit_cast(float, w.w & 0xffff0000u)}; }
;                         *(u32x4*)(outb + (size_t)row * 2048 + col) = pack8(b0 + g[bj][0] * acc[ai][bj][m][0], b1 + g[bj][1] * acc[ai][bj][m][1]); } } }
.LBB0_620:
	s_waitcnt vmcnt(10)
	v_pk_fma_f32 v[28:29], v[28:29], v[76:77], v[220:221]
	v_pk_fma_f32 v[32:33], v[26:27], v[74:75], v[218:219]
	v_pk_fma_f32 v[26:27], v[24:25], v[72:73], v[216:217]
	v_cvt_pk_bf16_f32 v24, v28, v29
	v_lshl_add_u64 v[28:29], s[12:13], 0, v[40:41]
	v_lshl_add_u64 v[28:29], v[166:167], 1, v[28:29]
	v_pk_fma_f32 v[30:31], v[30:31], v[78:79], v[222:223]
	s_nop 0
	v_cvt_pk_bf16_f32 v25, v30, v31
	v_cvt_pk_bf16_f32 v26, v26, v27
	v_cvt_pk_bf16_f32 v27, v32, v33
	global_store_dwordx4 v[28:29], v[24:27], off

;     __device__ __forceinline__ void operator()(const f32x4 (&acc)[2][2][4][2], const Unit& u, int wr, int wc, int fr, int fq) const {
;     ...
;             for (int m = 0; m < 4; ++m) { const int row = row0 + ai * HALF + m * 16;
; #pragma unroll
;                 for (int bj = 0; bj < 2; ++bj) { const int col = col0 + bj * HALF;
;                     if (u.split) { float* pp = part + ((size_t)(u.k0 / u.nt) * (MROWS - MP) + (size_t)(row - MP)) * 2048 + col;
;                         *(f32x4*)pp = g[bj][0] * acc[ai][bj][m][0]; *(f32x4*)(pp + 4) = g[bj][1] * acc[ai][bj][m][1];
;                     } else {
;                         f32x4 b0, b1;
;                         if (xp) { const float* src = xp + (size_t)row * 2048 + col; b0 = *(const f32x4*)src; b1 = *(const f32x4*)(src + 4); }
.LBB0_625:
.LBB0_626:
	s_andn2_b64 vcc, exec, s[22:23]
	s_cbranch_vccnz .LBB0_660
	v_lshl_add_u64 v[24:25], s[36:37], 0, v[44:45]
	v_lshl_add_u64 v[24:25], v[166:167], 2, v[24:25]
	s_nop 0
	s_nop 0
	s_nop 0
	s_cbranch_execnz .LBB0_629

; __device__ __forceinline__ u32x4 pack8(f32x4 v0, f32x4 v1) { u32x4 w; w.x = cvt_pk_bf16(v0[0], v0[1]); w.y = cvt_pk_bf16(v0[2], v0[3]); w.z = cvt_pk_bf16(v1[0], v1[1]); w.w = cvt_pk_bf16(v1[2], v1[3]); return w; }
;     __device__ __forceinline__ void operator()(const f32x4 (&acc)[2][2][4][2], const Unit& u, int wr, int wc, int fr, int fq) const {
;     ...
;                 for (int bj = 0; bj < 2; ++bj) { const int col = col0 + bj * HALF;
;                     if (u.split) { float* pp = part + ((size_t)(u.k0 / u.nt) * (MROWS - MP) + (size_t)(row - MP)) * 2048 + col;
;                         *(f32x4*)pp = g[bj][0] * acc[ai][bj][m][0]; *(f32x4*)(pp + 4) = g[bj][1] * acc[ai][bj][m][1];
;                     } else {
;                         f32x4 b0, b1;
;                         if (xp) { const float* src = xp + (size_t)row * 2048 + col; b0 = *(const f32x4*)src; b1 = *(const f32x4*)(src + 4); }
;                         else { const u32x4 w = *(const u32x4*)(baseb + (size_t)row * 2048 + col);
;                             b0 = (f32x4){__builtin_bit_cast(float, w.x << 16), __builtin_bit_cast(float, w.x & 0xffff0000u), __builtin_bit_cast(float, w.y << 16), __builtin_bit_cast(float, w.y & 0xffff0000u)};
;                             b1 = (f32x4){__builtin_bit_cast(float, w.z << 16), __builtin_bit_cast(float, w.z & 0xffff0000u), __builtin_bit_cast(float, w.w << 16), __builtin_bit_cast(float, w.w & 0xffff0000u)}; }
;                         *(u32x4*)(outb + (size_t)row * 2048 + col) = pack8(b0 + g[bj][0] * acc[ai][bj][m][0], b1 + g[bj][1] * acc[ai][bj][m][1]); } } }
.LBB0_629:
	s_waitcnt vmcnt(9)
	v_pk_fma_f32 v[20:21], v[20:21], v[68:69], v[228:229]
	v_pk_fma_f32 v[24:25], v[18:19], v[66:67], v[226:227]
	v_pk_fma_f32 v[18:19], v[16:17], v[64:65], v[224:225]
	v_cvt_pk_bf16_f32 v16, v20, v21
	v_lshl_add_u64 v[20:21], s[12:13], 0, v[40:41]
	v_lshl_add_u64 v[20:21], v[166:167], 1, v[20:21]
	v_pk_fma_f32 v[22:23], v[22:23], v[70:71], v[230:231]
	s_nop 0
	v_cvt_pk_bf16_f32 v17, v22, v23
	v_cvt_pk_bf16_f32 v18, v18, v19
	v_cvt_pk_bf16_f32 v19, v24, v25
	global_store_dwordx4 v[20:21], v[16:19], off offset:256
	s_nop 1
	v_lshlrev_b64 v[16:17], 13, v[168:169]
	s_and_b64 vcc, exec, s[4:5]
	v_lshl_add_u64 v[26:27], v[16:17], 0, s[48:49]
	s_cbranch_vccz .LBB0_624

;     __device__ __forceinline__ void operator()(const f32x4 (&acc)[2][2][4][2], const Unit& u, int wr, int wc, int fr, int fq) const {
;     ...
;             for (int m = 0; m < 4; ++m) { const int row = row0 + ai * HALF + m * 16;
; #pragma unroll
;                 for (int bj = 0; bj < 2; ++bj) { const int col = col0 + bj * HALF;
;                     if (u.split) { float* pp = part + ((size_t)(u.k0 / u.nt) * (MROWS - MP) + (size_t)(row - MP)) * 2048 + col;
;                         *(f32x4*)pp = g[bj][0] * acc[ai][bj][m][0]; *(f32x4*)(pp + 4) = g[bj][1] * acc[ai][bj][m][1];
;                     } else {
;                         f32x4 b0, b1;
;                         if (xp) { const float* src = xp + (size_t)row * 2048 + col; b0 = *(const f32x4*)src; b1 = *(const f32x4*)(src + 4); }
.LBB0_631:
	s_nop 0
	v_add_u32_e32 v16, 0xb0, v168
	v_ashrrev_i32_e32 v17, 31, v16
	v_lshlrev_b64 v[28:29], 13, v[16:17]
	s_andn2_b64 vcc, exec, s[60:61]
	v_lshlrev_b64 v[24:25], 12, v[16:17]
	s_cbranch_vccnz .LBB0_636
	s_andn2_b64 vcc, exec, s[22:23]
	s_cbranch_vccnz .LBB0_661
	v_lshl_add_u64 v[16:17], s[36:37], 0, v[28:29]
	v_lshl_add_u64 v[16:17], v[166:167], 2, v[16:17]
	s_nop 0
	s_nop 0
	s_nop 0
	s_cbranch_execnz .LBB0_635

; __device__ __forceinline__ u32x4 pack8(f32x4 v0, f32x4 v1) { u32x4 w; w.x = cvt_pk_bf16(v0[0], v0[1]); w.y = cvt_pk_bf16(v0[2], v0[3]); w.z = cvt_pk_bf16(v1[0], v1[1]); w.w = cvt_pk_bf16(v1[2], v1[3]); return w; }
;     __device__ __forceinline__ void operator()(const f32x4 (&acc)[2][2][4][2], const Unit& u, int wr, int wc, int fr, int fq) const {
;     ...
;                 for (int bj = 0; bj < 2; ++bj) { const int col = col0 + bj * HALF;
;                     if (u.split) { float* pp = part + ((size_t)(u.k0 / u.nt) * (MROWS - MP) + (size_t)(row - MP)) * 2048 + col;
;                         *(f32x4*)pp = g[bj][0] * acc[ai][bj][m][0]; *(f32x4*)(pp + 4) = g[bj][1] * acc[ai][bj][m][1];
;                     } else {
;                         f32x4 b0, b1;
;                         if (xp) { const float* src = xp + (size_t)row * 2048 + col; b0 = *(const f32x4*)src; b1 = *(const f32x4*)(src + 4); }
;                         else { const u32x4 w = *(const u32x4*)(baseb + (size_t)row * 2048 + col);
;                             b0 = (f32x4){__builtin_bit_cast(float, w.x << 16), __builtin_bit_cast(float, w.x & 0xffff0000u), __builtin_bit_cast(float, w.y << 16), __builtin_bit_cast(float, w.y & 0xffff0000u)};
;                             b1 = (f32x4){__builtin_bit_cast(float, w.z << 16), __builtin_bit_cast(float, w.z & 0xffff0000u), __builtin_bit_cast(float, w.w << 16), __builtin_bit_cast(float, w.w & 0xffff0000u)}; }
;                         *(u32x4*)(outb + (size_t)row * 2048 + col) = pack8(b0 + g[bj][0] * acc[ai][bj][m][0], b1 + g[bj][1] * acc[ai][bj][m][1]); } } }
.LBB0_635:
	s_waitcnt vmcnt(8)
	v_pk_fma_f32 v[12:13], v[12:13], v[76:77], v[236:237]
	v_pk_fma_f32 v[16:17], v[10:11], v[74:75], v[234:235]
	v_pk_fma_f32 v[10:11], v[8:9], v[72:73], v[232:233]
	v_cvt_pk_bf16_f32 v8, v12, v13
	v_lshl_add_u64 v[12:13], s[12:13], 0, v[24:25]
	v_lshl_add_u64 v[12:13], v[166:167], 1, v[12:13]
	v_pk_fma_f32 v[14:15], v[14:15], v[78:79], v[238:239]
	s_nop 0
	v_cvt_pk_bf16_f32 v9, v14, v15
	v_cvt_pk_bf16_f32 v10, v10, v11
	v_cvt_pk_bf16_f32 v11, v16, v17
	global_store_dwordx4 v[12:13], v[8:11], off

;     __device__ __forceinline__ void operator()(const f32x4 (&acc)[2][2][4][2], const Unit& u, int wr, int wc, int fr, int fq) const {
;     ...
;             for (int m = 0; m < 4; ++m) { const int row = row0 + ai * HALF + m * 16;
; #pragma unroll
;                 for (int bj = 0; bj < 2; ++bj) { const int col = col0 + bj * HALF;
;                     if (u.split) { float* pp = part + ((size_t)(u.k0 / u.nt) * (MROWS - MP) + (size_t)(row - MP)) * 2048 + col;
;                         *(f32x4*)pp = g[bj][0] * acc[ai][bj][m][0]; *(f32x4*)(pp + 4) = g[bj][1] * acc[ai][bj][m][1];
;                     } else {
;                         f32x4 b0, b1;
;                         if (xp) { const float* src = xp + (size_t)row * 2048 + col; b0 = *(const f32x4*)src; b1 = *(const f32x4*)(src + 4); }
.LBB0_639:
.LBB0_640:
	s_andn2_b64 vcc, exec, s[22:23]
	s_cbranch_vccnz .LBB0_662
	v_lshl_add_u64 v[8:9], s[36:37], 0, v[28:29]
	v_lshl_add_u64 v[8:9], v[166:167], 2, v[8:9]
	s_nop 0
	s_nop 0
	s_nop 0
	s_cbranch_execnz .LBB0_643

; __device__ __forceinline__ u32x4 pack8(f32x4 v0, f32x4 v1) { u32x4 w; w.x = cvt_pk_bf16(v0[0], v0[1]); w.y = cvt_pk_bf16(v0[2], v0[3]); w.z = cvt_pk_bf16(v1[0], v1[1]); w.w = cvt_pk_bf16(v1[2], v1[3]); return w; }
;     __device__ __forceinline__ void operator()(const f32x4 (&acc)[2][2][4][2], const Unit& u, int wr, int wc, int fr, int fq) const {
;     ...
;                 for (int bj = 0; bj < 2; ++bj) { const int col = col0 + bj * HALF;
;                     if (u.split) { float* pp = part + ((size_t)(u.k0 / u.nt) * (MROWS - MP) + (size_t)(row - MP)) * 2048 + col;
;                         *(f32x4*)pp = g[bj][0] * acc[ai][bj][m][0]; *(f32x4*)(pp + 4) = g[bj][1] * acc[ai][bj][m][1];
;                     } else {
;                         f32x4 b0, b1;
;                         if (xp) { const float* src = xp + (size_t)row * 2048 + col; b0 = *(const f32x4*)src; b1 = *(const f32x4*)(src + 4); }
;                         else { const u32x4 w = *(const u32x4*)(baseb + (size_t)row * 2048 + col);
;                             b0 = (f32x4){__builtin_bit_cast(float, w.x << 16), __builtin_bit_cast(float, w.x & 0xffff0000u), __builtin_bit_cast(float, w.y << 16), __builtin_bit_cast(float, w.y & 0xffff0000u)};
;                             b1 = (f32x4){__builtin_bit_cast(float, w.z << 16), __builtin_bit_cast(float, w.z & 0xffff0000u), __builtin_bit_cast(float, w.w << 16), __builtin_bit_cast(float, w.w & 0xffff0000u)}; }
;                         *(u32x4*)(outb + (size_t)row * 2048 + col) = pack8(b0 + g[bj][0] * acc[ai][bj][m][0], b1 + g[bj][1] * acc[ai][bj][m][1]); } } }
.LBB0_643:
	s_waitcnt vmcnt(7)
	v_pk_fma_f32 v[4:5], v[4:5], v[68:69], v[244:245]
	v_pk_fma_f32 v[8:9], v[2:3], v[66:67], v[242:243]
	v_pk_fma_f32 v[2:3], v[0:1], v[64:65], v[240:241]
	v_cvt_pk_bf16_f32 v0, v4, v5
	v_lshl_add_u64 v[4:5], s[12:13], 0, v[24:25]
	v_lshl_add_u64 v[4:5], v[166:167], 1, v[4:5]
	v_pk_fma_f32 v[6:7], v[6:7], v[70:71], v[246:247]
	s_nop 0
	v_cvt_pk_bf16_f32 v1, v6, v7
	v_cvt_pk_bf16_f32 v2, v2, v3
	v_cvt_pk_bf16_f32 v3, v8, v9
	global_store_dwordx4 v[4:5], v[0:3], off offset:256
	s_and_b64 vcc, exec, s[0:1]
	s_mov_b64 s[0:1], -1
	s_cbranch_vccnz .LBB0_506
